# even attention: one global item queue again (chains stay pinned); per-XCD queues dropped
# baseline (speedup 1.0000x reference)
.Lxq_fetch:
	s_mov_b32 s8, 0
	v_mov_b32_e32 v2, 1
	v_mov_b32_e32 v5, s8
	s_waitcnt vmcnt(0)
	global_atomic_add v2, v5, v2, s[6:7] sc0
	s_waitcnt vmcnt(0)
	v_readfirstlane_b32 s8, v2
	s_cmpk_lt_u32 s8, 0x700
	s_cbranch_scc1 .Lxq_got
	s_movk_i32 s8, 0x720
	s_branch .Lxq_put
.Lxq_got:
	s_add_u32 s8, s8, 32
